# phase-scoped priority: the first half's raised priority is dropped from P2 onward (equal priority for the two independent halves in P2 and P3)
# speedup vs baseline: 1.0009x; 1.0009x over previous
; __device__ __forceinline__ int vblk() { return (int)blockIdx.x * 2 + half_id(); }
; __device__ __forceinline__ int vgrid() { return (int)gridDim.x * 2; }
; #define PF fresh_params()
; __global__ void __launch_bounds__(BLOCK_THREADS, 2) mega(Params p_unused) {
;     ...
;     {
;         const int vg = vgrid(), gsz = (vg & 7) == 0 ? 4 : 1;
;         for (int t0 = vblk(); t0 < 2048; t0 += gsz * vg) {
;             const int rem = (2048 - t0 + vg - 1) / vg;
;             phaseP2_group(PF, t0, vg, rem < gsz ? rem : gsz, hl);
;         }
.LBB0_973:
	s_or_b64 exec, exec, s[4:5]
	s_setprio 0
	s_getpc_b64 s[98:99]
	v_lshlrev_b32_e32 v250, 4, v158
	v_mov_b32_e32 v251, 0
	v_lshl_add_u64 v[250:251], s[98:99], 0, v[250:251]
	v_and_b32_e32 v250, -16, v250
	global_load_dwordx4 v[252:255], v[250:251], off
	v_lshl_add_u64 v[250:251], 64, 7, v[250:251]
	global_load_dwordx4 v[252:255], v[250:251], off
	v_readfirstlane_b32 s0, v158
	s_lshr_b32 s0, s0, 8
	s_add_i32 s0, s0, s77
	s_cmpk_gt_i32 s0, 0x7ff
	s_waitcnt lgkmcnt(0)
	s_barrier
	s_getpc_b64 s[98:99]
	v_lshlrev_b32_e32 v250, 4, v158
	v_mov_b32_e32 v251, 0
	v_lshl_add_u64 v[250:251], s[98:99], 0, v[250:251]
	v_and_b32_e32 v250, -16, v250
	global_load_dwordx4 v[252:255], v[250:251], off
	v_lshl_add_u64 v[250:251], 64, 7, v[250:251]
	global_load_dwordx4 v[252:255], v[250:251], off
	s_cbranch_scc1 .LBB0_989
	s_lshl_b32 s1, s72, 1
	s_and_b32 s3, s72, 3
	s_add_i32 s2, s1, 0x7ff
	s_cmp_eq_u32 s3, 0
	s_cselect_b32 s3, 4, 1
	s_cselect_b32 s4, 2, 0
	s_abs_i32 s24, s1
	v_cvt_f32_u32_e32 v0, s24
	s_lshl_b32 s27, s1, s4
	s_sub_i32 s4, 0, s24
	s_add_i32 s5, s0, s1
	v_rcp_iflag_f32_e32 v0, v0
	s_mov_b32 s9, 0
	s_bfe_i32 s25, s72, 0x1001e
	s_add_i32 s26, s33, 0x8000
	v_mul_f32_e32 v0, 0x4f7ffffe, v0
	v_cvt_u32_f32_e32 v0, v0
	s_lshl_b32 s29, s5, 3
	s_lshl_b32 s30, s27, 3
	s_lshl_b32 s31, s72, 4
	v_readfirstlane_b32 s6, v0
	s_mul_i32 s4, s4, s6
	s_mul_hi_u32 s4, s6, s4
	s_add_i32 s28, s6, s4
	s_movk_i32 s34, 0xffc0
	v_mov_b32_e32 v33, 0
	s_mov_b64 s[10:11], 0x234000
	s_movk_i32 s35, 0x7f
	s_movk_i32 s36, 0x3fff
	s_mov_b64 s[12:13], 0xdd00000
	s_mov_b64 s[14:15], 0xe500000
	s_mov_b32 s37, 0xdd00000
	s_mov_b32 s38, 0xe500000
	s_branch .LBB0_976
